# gdn_seq: chunk operands prefetched two steps ahead (second staging register set), far out-of-line blocks moved next to gdn_prep
# baseline (speedup 1.0000x reference)
; __device__ __forceinline__ void gdn_prep(LAS unsigned char* ldsb, bf16_t* P, const bf16_t* HALO, const float* BA, const float* conv_w, const float* a_log, const float* dt_bias,
;                                          bf16_t* Wbuf, bf16_t* ATT, float* GATES) {
;     ...
;     if ((int)blockIdx.x < 4096) PREP_LOAD((int)blockIdx.x);
.LBB0_1223:
	v_mov_b32_e32 v47, 0
	v_mov_b32_e32 v46, v47
	v_mov_b32_e32 v45, v47
	v_mov_b32_e32 v44, v47
	s_andn2_saveexec_b64 s[70:71], s[78:79]
	s_cbranch_execnz .LBB0_1016
	s_branch .LBB0_1017
.LBB0_1995:
	v_mov_b32_e32 v20, 0
	v_mov_b32_e32 v21, v20
	v_mov_b32_e32 v22, v20
	v_mov_b32_e32 v23, v20
	s_andn2_saveexec_b64 s[66:67], s[66:67]
	s_cbranch_execz .LBB0_2002
	s_getpc_b64 s[98:99]

; __device__ __forceinline__ unsigned xb_ld(unsigned* p)              { return __hip_atomic_load(p, __ATOMIC_RELAXED, __HIP_MEMORY_SCOPE_AGENT); }
; __device__ __forceinline__ unsigned xb_add(unsigned* p, unsigned v) { return __hip_atomic_fetch_add(p, v, __ATOMIC_RELAXED, __HIP_MEMORY_SCOPE_AGENT); }
; __device__ __forceinline__ void xcd_barrier_complete(unsigned* bar, unsigned x, unsigned& nloc, unsigned& nx) {
;     const unsigned G = gridDim.x * gridDim.y * gridDim.z;
;     unsigned sum, cnt, mine, sp = 0u;
;     for (;;) {
;         sum = 0u; cnt = 0u; mine = 0u;
; #pragma unroll
;         for (unsigned j = 0; j < 16; ++j) { const unsigned c = xb_ld(&bar[XB_XCNT(j)]); sum += c; cnt += (c > 0u) ? 1u : 0u; mine = (j == x) ? c : mine; }
; __device__ __forceinline__ void xcd_barrier(const XcdBarrier& b) {
;     asm volatile("s_waitcnt vmcnt(0)" ::: "memory");
;     __syncthreads();
;     if (threadIdx.x == 0) {
;         unsigned* bar = b.bar;
;         __builtin_amdgcn_s_waitcnt(0);
;         unsigned nloc = b.st[0], nx = b.st[1];
;         if (nloc == 0u) { xcd_barrier_complete(bar, b.x, nloc, nx); b.st[0] = nloc; b.st[1] = nx; }
;         const unsigned old = xb_add(&bar[XB_XSUB(b.x)], 1u);
.LBB0_2001:
	v_mov_b32_e32 v47, 0
	v_mov_b32_e32 v46, v47
	v_mov_b32_e32 v45, v47
	v_mov_b32_e32 v44, v47
	s_andn2_saveexec_b64 s[10:11], s[66:67]
	s_cbranch_execnz .LBB0_935
	s_branch .LBB0_936
.LBB0_1224:
	s_waitcnt vmcnt(0)
	v_readlane_b32 s0, v242, 7
	v_readlane_b32 s1, v242, 8
	s_waitcnt lgkmcnt(0)
	s_barrier
	s_and_saveexec_b64 s[6:7], s[0:1]
	s_cbranch_execz .LBB0_1276
	s_add_i32 s4, 0, 0x248f0
	v_mov_b32_e32 v0, s4
	s_waitcnt vmcnt(0) expcnt(0) lgkmcnt(0)
	ds_read_b32 v2, v0
	s_add_i32 s4, 0, 0x248f4
	v_mov_b32_e32 v0, s4
	ds_read_b32 v0, v0
	s_waitcnt lgkmcnt(1)
	v_cmp_ne_u32_e32 vcc, 0, v2
	s_cbranch_vccnz .LBB0_1240
	s_add_u32 s8, s26, 0x80200
	s_addc_u32 s9, s27, 0
	s_add_u32 s10, s26, 0x80400
	s_addc_u32 s11, s27, 0
	s_add_u32 s12, s26, 0x80500
	s_addc_u32 s13, s27, 0
	s_add_u32 s14, s26, 0x80600
	s_addc_u32 s15, s27, 0
	s_add_u32 s16, s26, 0x80700
	s_addc_u32 s17, s27, 0
	s_add_u32 s64, s26, 0x80800
	s_addc_u32 s65, s27, 0
	s_add_u32 s66, s26, 0x80900
	s_addc_u32 s67, s27, 0
	s_add_u32 s68, s26, 0x80a00
	s_addc_u32 s69, s27, 0
	s_add_u32 s70, s26, 0x80b00
	s_addc_u32 s71, s27, 0
	s_add_u32 s72, s26, 0x80c00
	s_addc_u32 s73, s27, 0
	s_add_u32 s74, s26, 0x80d00
	s_addc_u32 s75, s27, 0
	s_add_u32 s76, s26, 0x80e00
	s_addc_u32 s77, s27, 0
	s_add_u32 s78, s26, 0x80f00
	s_addc_u32 s79, s27, 0
	s_add_u32 s80, s26, 0x81000
	s_addc_u32 s81, s27, 0
	s_add_u32 s82, s26, 0x81100
	s_addc_u32 s83, s27, 0
	v_readlane_b32 s0, v242, 1
	s_add_u32 s84, s26, 0x81200
	v_readlane_b32 s1, v242, 2
	v_readlane_b32 s4, v242, 0
	s_addc_u32 s85, s27, 0
	s_mul_i32 s4, s1, s4
	s_add_u32 s86, s26, 0x81300
	s_mul_i32 s4, s4, s0
	s_addc_u32 s87, s27, 0
	s_mov_b32 s5, 1
	v_mov_b32_e32 v16, 0
	s_branch .LBB0_1228

; __device__ __forceinline__ void gdn_seq(LAS unsigned char* ldsb, bf16_t* P, const bf16_t* Wbuf, const bf16_t* ATT, const float* GATES, const bool wr_out) {
;     ...
;         __syncthreads();
;         for (int idx = tid; idx < 32 * 136; idx += 512) sSt[idx] = 0;
;         f32x16 sacc; for (int i = 0; i < 16; ++i) sacc[i] = 0.f;
;         GS_LOAD(0);
;         GS_STORE(0);
;         GS_LOAD(1);
;         __syncthreads();
.LBB0_1294:
	s_or_b64 exec, exec, s[18:19]
	s_lshr_b32 s16, s96, 5
	s_and_b32 s16, s16, 7
	s_lshl_b32 s18, s16, 9
	s_lshl_b32 s19, s16, 13
	s_lshl_b32 s34, s16, 8
	s_lshl_b64 s[16:17], s[14:15], 12
	s_lshl_b64 s[14:15], s[14:15], 16
	s_or_b32 s14, s14, s19
	v_lshl_add_u64 v[134:135], s[14:15], 0, v[110:111]
	s_lshl_b32 s14, s96, 3
	s_or_b32 s16, s16, s18
	s_and_b32 s14, s14, 0xc0
	v_lshl_add_u64 v[132:133], s[16:17], 0, v[108:109]
	s_mul_i32 s16, s12, 0x2600000
	s_or_b32 s14, s14, s34
	s_mul_hi_i32 s15, s12, 0x2600000
	s_or_b32 s14, s16, s14
	s_lshl_b64 s[12:13], s[12:13], 23
	v_mov_b32_e32 v14, v1
	v_mov_b32_e32 v15, v1
	v_lshl_add_u64 v[136:137], s[14:15], 0, v[112:113]
	s_or_b32 s14, s16, s34
	s_or_b32 s12, s12, s34
	v_mov_b32_e32 v0, v1
	v_mov_b32_e32 v2, v1
	v_mov_b32_e32 v3, v1
	v_mov_b32_e32 v4, v1
	v_mov_b32_e32 v5, v1
	v_mov_b32_e32 v6, v1
	v_mov_b32_e32 v7, v1
	v_mov_b32_e32 v8, v1
	v_mov_b32_e32 v9, v1
	v_mov_b32_e32 v10, v1
	v_mov_b32_e32 v11, v1
	v_mov_b32_e32 v12, v1
	v_mov_b32_e32 v13, v1
	v_mov_b64_e32 v[32:33], v[14:15]
	s_lshl_b32 s97, s97, 5
	v_lshl_add_u64 v[138:139], s[14:15], 0, v[114:115]
	v_lshl_add_u64 v[140:141], s[14:15], 0, v[116:117]
	v_lshl_add_u64 v[142:143], s[12:13], 0, v[118:119]
	v_lshl_add_u64 v[144:145], s[14:15], 0, v[120:121]
	v_lshl_add_u64 v[146:147], s[14:15], 0, v[122:123]
	v_lshl_add_u64 v[148:149], s[12:13], 0, v[124:125]
	s_mov_b32 s16, 0
	s_mov_b32 s17, s5
	v_mov_b64_e32 v[30:31], v[12:13]
	v_mov_b64_e32 v[28:29], v[10:11]
	v_mov_b64_e32 v[26:27], v[8:9]
	v_mov_b64_e32 v[24:25], v[6:7]
	v_mov_b64_e32 v[22:23], v[4:5]
	v_mov_b64_e32 v[20:21], v[2:3]
	v_mov_b64_e32 v[18:19], v[0:1]
	s_waitcnt lgkmcnt(0)
	s_barrier
	v_lshl_add_u64 v[2:3], s[26:27], 0, v[148:149]
	v_lshl_add_u64 v[4:5], s[26:27], 0, v[144:145]
	global_load_dwordx4 v[222:225], v[2:3], off
	global_load_dwordx4 v[226:229], v[4:5], off
	v_lshl_add_u64 v[2:3], s[26:27], 0, v[146:147]
	v_lshl_add_u64 v[4:5], s[26:27], 0, v[142:143]
	global_load_dwordx4 v[236:239], v[2:3], off
	global_load_dwordx4 v[232:235], v[4:5], off
	v_lshl_add_u64 v[2:3], s[26:27], 0, v[138:139]
	v_lshl_add_u64 v[4:5], s[26:27], 0, v[140:141]
	global_load_dwordx4 v[248:251], v[2:3], off
	global_load_dwordx4 v[244:247], v[4:5], off
	v_lshl_add_u64 v[2:3], s[26:27], 0, v[134:135]
	global_load_dwordx4 v[252:255], v[2:3], off
	s_and_saveexec_b64 s[14:15], s[8:9]
	s_cbranch_execz .LBB0_1306_p
	v_lshl_add_u64 v[2:3], s[26:27], 0, v[136:137]
	global_load_dwordx4 v[112:115], v[2:3], off
	s_or_b64 exec, exec, s[14:15]
	s_and_saveexec_b64 s[14:15], s[10:11]
	s_cbranch_execz .LBB0_1308_p
	s_branch .LBB0_1307_p

.LBB0_1307_p:
	v_lshl_add_u64 v[2:3], s[26:27], 0, v[132:133]
	global_load_dwordx4 v[108:111], v[2:3], off
.LBB0_1308_p:
	s_or_b64 exec, exec, s[14:15]
	s_mov_b64 s[14:15], 0x1000
	v_lshl_add_u64 v[132:133], v[132:133], 0, s[14:15]
	s_mov_b64 s[14:15], 0x10000
	v_lshl_add_u64 v[134:135], v[134:135], 0, s[14:15]
	v_lshl_add_u64 v[136:137], v[136:137], 0, s[74:75]
	v_lshl_add_u64 v[138:139], v[138:139], 0, s[74:75]
	v_lshl_add_u64 v[140:141], v[140:141], 0, s[74:75]
	v_lshl_add_u64 v[142:143], v[142:143], 0, s[76:77]
	v_lshl_add_u64 v[144:145], v[144:145], 0, s[74:75]
	v_lshl_add_u64 v[146:147], v[146:147], 0, s[74:75]
	v_lshl_add_u64 v[148:149], v[148:149], 0, s[76:77]

; __device__ __forceinline__ void gdn_seq(LAS unsigned char* ldsb, bf16_t* P, const bf16_t* Wbuf, const bf16_t* ATT, const float* GATES, const bool wr_out) {
;     ...
;             if (n + 1 < 64) { GS_STORE(cur ^ 1); if (n + 2 < 64) GS_LOAD(n + 2); }
.LBB0_1300:
	s_xor_b32 s34, s18, 1
	s_mul_i32 s14, s34, 0x4800
	v_add_u32_e32 v0, s14, v87
	s_nop 5
	v_add_u32_e32 v2, v0, v95
	v_add_u32_e32 v0, v0, v103
	s_mul_i32 s14, s34, 0x2400
	s_waitcnt lgkmcnt(0)
	s_barrier
	s_and_b64 vcc, exec, s[70:71]
	s_cbranch_vccnz .Lseq_norm_e
	s_cmp_lt_u32 s16, 2
	s_cbranch_scc1 .Lseq_norm_e
	s_waitcnt vmcnt(47)
	ds_write_b128 v102, v[58:61]
	s_waitcnt vmcnt(46)
	ds_write_b128 v102, v[62:65] offset:17408
	s_waitcnt vmcnt(45)
	ds_write_b128 v2, v[70:73] offset:34816
	s_waitcnt vmcnt(44)
	ds_write_b128 v104, v[66:69]
	s_waitcnt vmcnt(43)
	ds_write_b128 v104, v[78:81] offset:17408
	s_waitcnt vmcnt(42)
	ds_write_b128 v0, v[74:77] offset:34816
	v_add_u32_e32 v0, s14, v150
	s_waitcnt vmcnt(40)
	ds_write_b128 v0, v[82:85]
	s_branch .Lseq_join_e
.Lseq_norm_e:
	s_waitcnt vmcnt(13)
	ds_write_b128 v102, v[58:61]
	s_waitcnt vmcnt(12)
	ds_write_b128 v102, v[62:65] offset:17408
	s_waitcnt vmcnt(11)
	ds_write_b128 v2, v[70:73] offset:34816
	s_waitcnt vmcnt(10)
	ds_write_b128 v104, v[66:69]
	s_waitcnt vmcnt(9)
	ds_write_b128 v104, v[78:81] offset:17408
	s_waitcnt vmcnt(8)
	ds_write_b128 v0, v[74:77] offset:34816
	v_add_u32_e32 v0, s14, v150
	s_waitcnt vmcnt(7)
	ds_write_b128 v0, v[82:85]
.Lseq_join_e:
	s_and_saveexec_b64 s[14:15], s[8:9]
	s_mul_i32 s35, s34, 0x1400
	v_add_u32_e32 v0, s35, v151
	ds_write_b128 v0, v[54:57]
	s_or_b64 exec, exec, s[14:15]
	s_and_saveexec_b64 s[14:15], s[10:11]
	v_lshl_add_u32 v0, s34, 9, v152
	ds_write_b128 v0, v[50:53]
	s_or_b64 exec, exec, s[14:15]
	v_lshl_add_u64 v[2:3], s[26:27], 0, v[148:149]
	v_lshl_add_u64 v[4:5], s[26:27], 0, v[144:145]
	global_load_dwordx4 v[58:61], v[2:3], off
	global_load_dwordx4 v[62:65], v[4:5], off
	v_lshl_add_u64 v[2:3], s[26:27], 0, v[146:147]
	v_lshl_add_u64 v[4:5], s[26:27], 0, v[142:143]
	global_load_dwordx4 v[70:73], v[2:3], off
	global_load_dwordx4 v[66:69], v[4:5], off
	v_lshl_add_u64 v[2:3], s[26:27], 0, v[138:139]
	v_lshl_add_u64 v[4:5], s[26:27], 0, v[140:141]
	global_load_dwordx4 v[78:81], v[2:3], off
	global_load_dwordx4 v[74:77], v[4:5], off
	v_lshl_add_u64 v[2:3], s[26:27], 0, v[134:135]
	global_load_dwordx4 v[82:85], v[2:3], off
	s_and_saveexec_b64 s[14:15], s[8:9]
	s_cbranch_execz .LBB0_1306
	v_lshl_add_u64 v[2:3], s[26:27], 0, v[136:137]
	global_load_dwordx4 v[54:57], v[2:3], off
	s_or_b64 exec, exec, s[14:15]
	s_and_saveexec_b64 s[14:15], s[10:11]
	s_cbranch_execz .LBB0_1308
	s_branch .LBB0_1307

; template <int KS> DI void mma_tile(f32x16& acc, const LAS bf16_t* As, int sa, const LAS bf16_t* Bs, int sb, int r, int hh) {
;     const unsigned aa = (unsigned)(size_t)(As + r * sa + hh * 8), ba = (unsigned)(size_t)(Bs + r * sb + hh * 8);
;     bf16x8 fa[KS], fb[KS];
;     constexpr int FIRST = KS < 7 ? KS : 7;
; #pragma unroll
;     for (int ks = 0; ks < FIRST; ++ks) {
;         asm volatile("ds_read_b128 %0, %1 offset:%2" : "=&v"(fa[ks]) : "v"(aa), "n"(ks * 32) : "memory");
;         asm volatile("ds_read_b128 %0, %1 offset:%2" : "=&v"(fb[ks]) : "v"(ba), "n"(ks * 32) : "memory");
;     }
; #pragma unroll
;     for (int ks = 0; ks < KS; ++ks) {
;         if (ks == 0) asm volatile("s_waitcnt lgkmcnt(%2)" : "+v"(fa[0]), "+v"(fb[0]) : "n"(2 * (FIRST - 1)) : "memory");
;         else asm volatile("s_waitcnt lgkmcnt(%2)" : "+v"(fa[ks]), "+v"(fb[ks]) : "n"(2 * (KS - 1 - ks)) : "memory");
;         acc = __builtin_amdgcn_mfma_f32_32x32x16_bf16(fa[ks], fb[ks], acc, 0, 0, 0);
; __device__ __forceinline__ void gdn_seq(LAS unsigned char* ldsb, bf16_t* P, const bf16_t* Wbuf, const bf16_t* ATT, const float* GATES, const bool wr_out) {
;     ...
;         for (int n = 0; n < 64; ++n) {
;             const int cur = n & 1;
;             const LAS float* gcur = sG + cur * 128;
;             f32x16 oacc; for (int i = 0; i < 16; ++i) oacc[i] = 0.f;
;             if (w < 4) {
;                 f32x16 acc; for (int i = 0; i < 16; ++i) acc[i] = 0.f;
;                 mma_tile<8>(acc, (w < 2 ? sW : sQ) + (w & 1) * 32 * 136, 136, sSt, 136, r, hh);
;                 if (w < 2) {
; #pragma unroll
;                     for (int g4 = 0; g4 < 4; ++g4) { float a[4], bsc[4];
; #pragma unroll
;                         for (int j = 0; j < 4; ++j) { const int i = g4 * 4 + j, c = (w & 1) * 32 + crow(i, hh); a[j] = bf2f(sU[cur * 2560 + c * 40 + r]) - acc[i]; bsc[j] = a[j] * gcur[64 + c]; }
;                         u32x2 p0, p1; p0.x = pk2(a[0], a[1]); p0.y = pk2(a[2], a[3]); p1.x = pk2(bsc[0], bsc[1]); p1.y = pk2(bsc[2], bsc[3]);
;                         *(LAS u32x2*)(sVT + r * 72 + (w & 1) * 32 + 8 * g4 + 4 * hh) = p0; *(LAS u32x2*)(sVTs + r * 72 + (w & 1) * 32 + 8 * g4 + 4 * hh) = p1; }
;                 } else {
; #pragma unroll
;                     for (int i = 0; i < 16; ++i) { const int c = (w & 1) * 32 + crow(i, hh); oacc[i] = gcur[c] * acc[i]; }
;                 }
;             }
.LBB0_1314:
	s_mov_b64 s[14:15], 0x1000
	s_add_i32 s16, s16, 1
	v_lshl_add_u64 v[132:133], v[132:133], 0, s[14:15]
	s_mov_b64 s[14:15], 0x10000
	s_add_i32 s17, s17, 64
	v_lshl_add_u64 v[134:135], v[134:135], 0, s[14:15]
	v_lshl_add_u64 v[136:137], v[136:137], 0, s[74:75]
	v_lshl_add_u64 v[138:139], v[138:139], 0, s[74:75]
	v_lshl_add_u64 v[140:141], v[140:141], 0, s[74:75]
	v_lshl_add_u64 v[142:143], v[142:143], 0, s[76:77]
	v_lshl_add_u64 v[144:145], v[144:145], 0, s[74:75]
	v_lshl_add_u64 v[146:147], v[146:147], 0, s[74:75]
	s_cmp_eq_u32 s16, 62
	v_lshl_add_u64 v[148:149], v[148:149], 0, s[76:77]
	s_waitcnt lgkmcnt(0)
	s_barrier
	s_cbranch_scc1 .LBB0_1316
	v_mov_b64_e32 v[32:33], v[16:17]
	v_mov_b64_e32 v[30:31], v[14:15]
	v_mov_b64_e32 v[28:29], v[12:13]
	v_mov_b64_e32 v[26:27], v[10:11]
	v_mov_b64_e32 v[24:25], v[8:9]
	v_mov_b64_e32 v[22:23], v[6:7]
	v_mov_b64_e32 v[20:21], v[4:5]
	v_mov_b64_e32 v[18:19], v[2:3]
	s_branch .LBB0_1295_o
.LBB0_1295_o:
	s_and_b32 s18, s16, 1
	s_lshl_b32 s12, s18, 9
	s_add_i32 s19, s12, 0
	v_cndmask_b32_e64 v0, 0, 1, s[66:67]
	s_add_i32 s19, s19, 0x18800
	v_mov_b32_e32 v34, 0
	v_cmp_ne_u32_e64 s[12:13], 1, v0
	s_andn2_b64 vcc, exec, s[66:67]
	v_mov_b32_e32 v35, 0
	v_mov_b32_e32 v36, 0
	v_mov_b32_e32 v37, 0
	v_mov_b32_e32 v38, 0
	v_mov_b32_e32 v39, 0
	v_mov_b32_e32 v40, 0
	v_mov_b32_e32 v41, 0
	v_mov_b32_e32 v42, 0
	v_mov_b32_e32 v43, 0
	v_mov_b32_e32 v44, 0
	v_mov_b32_e32 v45, 0
	v_mov_b32_e32 v46, 0
	v_mov_b32_e32 v47, 0
	v_mov_b32_e32 v48, 0
	v_mov_b32_e32 v49, 0
	s_cbranch_vccnz .LBB0_1300_o
	ds_read_b128 v[2:5], v155 offset:0
	ds_read_b128 v[6:9], v156 offset:0
	ds_read_b128 v[34:37], v155 offset:32
	ds_read_b128 v[38:41], v156 offset:32
	ds_read_b128 v[42:45], v155 offset:64
	ds_read_b128 v[46:49], v156 offset:64
	ds_read_b128 v[182:185], v155 offset:0x60
	ds_read_b128 v[186:189], v156 offset:0x60
	ds_read_b128 v[190:193], v155 offset:0x80
	ds_read_b128 v[194:197], v156 offset:0x80
	ds_read_b128 v[198:201], v155 offset:0xa0
	ds_read_b128 v[202:205], v156 offset:0xa0
	ds_read_b128 v[206:209], v155 offset:0xc0
	ds_read_b128 v[210:213], v156 offset:0xc0
	s_nop 0
	s_waitcnt lgkmcnt(12)
	ds_read_b128 v[214:217], v155 offset:0xe0
	ds_read_b128 v[218:221], v156 offset:0xe0
	s_waitcnt lgkmcnt(12)
	s_waitcnt lgkmcnt(10)
	s_waitcnt lgkmcnt(8)
	s_nop 0
	v_mfma_f32_32x32x16_bf16 v[2:17], v[2:5], v[6:9], 0
	s_waitcnt lgkmcnt(6)
	s_waitcnt lgkmcnt(4)
	s_waitcnt lgkmcnt(2)
	s_waitcnt lgkmcnt(0)
	s_andn2_b64 vcc, exec, s[68:69]
	s_mov_b64 s[14:15], -1
	v_mfma_f32_32x32x16_bf16 v[2:17], v[34:37], v[38:41], v[2:17]
	v_mfma_f32_32x32x16_bf16 v[2:17], v[42:45], v[46:49], v[2:17]
	v_mfma_f32_32x32x16_bf16 v[2:17], v[182:185], v[186:189], v[2:17]
	v_mfma_f32_32x32x16_bf16 v[2:17], v[190:193], v[194:197], v[2:17]
	v_mfma_f32_32x32x16_bf16 v[2:17], v[198:201], v[202:205], v[2:17]
	v_mfma_f32_32x32x16_bf16 v[2:17], v[206:209], v[210:213], v[2:17]
	v_mfma_f32_32x32x16_bf16 v[2:17], v[214:217], v[218:221], v[2:17]
	s_cbranch_vccnz .LBB0_1298_o
	s_add_i32 s14, s19, s20
	v_add_u32_e32 v0, s14, v154
	ds_read_b128 v[34:37], v0 offset:96
	ds_read_b128 v[38:41], v0 offset:64
	ds_read_b128 v[182:185], v0
	ds_read_b128 v[186:189], v0 offset:32
	s_mov_b64 s[14:15], 0
	s_waitcnt lgkmcnt(3)
	s_nop 2
	v_pk_mul_f32 v[48:49], v[16:17], v[36:37]
	v_pk_mul_f32 v[46:47], v[14:15], v[34:35]
	s_waitcnt lgkmcnt(2)
	v_pk_mul_f32 v[44:45], v[12:13], v[40:41]
	v_pk_mul_f32 v[42:43], v[10:11], v[38:39]
	s_waitcnt lgkmcnt(0)
	v_pk_mul_f32 v[40:41], v[8:9], v[188:189]
	v_pk_mul_f32 v[38:39], v[6:7], v[186:187]
	v_pk_mul_f32 v[36:37], v[4:5], v[184:185]
	v_pk_mul_f32 v[34:35], v[2:3], v[182:183]

; __device__ __forceinline__ void gdn_seq(LAS unsigned char* ldsb, bf16_t* P, const bf16_t* Wbuf, const bf16_t* ATT, const float* GATES, const bool wr_out) {
;     ...
;             if (n + 1 < 64) { GS_STORE(cur ^ 1); if (n + 2 < 64) GS_LOAD(n + 2); }
.LBB0_1300_o:
	s_xor_b32 s34, s18, 1
	s_mul_i32 s14, s34, 0x4800
	v_add_u32_e32 v0, s14, v87
	s_nop 5
	v_add_u32_e32 v2, v0, v95
	v_add_u32_e32 v0, v0, v103
	s_mul_i32 s14, s34, 0x2400
	s_waitcnt lgkmcnt(0)
	s_barrier
	s_and_b64 vcc, exec, s[70:71]
	s_cbranch_vccnz .Lseq_norm_o
	s_cmp_lt_u32 s16, 2
	s_cbranch_scc1 .Lseq_norm_o
	s_waitcnt vmcnt(47)
	ds_write_b128 v102, v[222:225]
	s_waitcnt vmcnt(46)
	ds_write_b128 v102, v[226:229] offset:17408
	s_waitcnt vmcnt(45)
	ds_write_b128 v2, v[236:239] offset:34816
	s_waitcnt vmcnt(44)
	ds_write_b128 v104, v[232:235]
	s_waitcnt vmcnt(43)
	ds_write_b128 v104, v[248:251] offset:17408
	s_waitcnt vmcnt(42)
	ds_write_b128 v0, v[244:247] offset:34816
	v_add_u32_e32 v0, s14, v150
	s_waitcnt vmcnt(40)
	ds_write_b128 v0, v[252:255]
	s_branch .Lseq_join_o
.Lseq_norm_o:
	s_waitcnt vmcnt(13)
	ds_write_b128 v102, v[222:225]
	s_waitcnt vmcnt(12)
	ds_write_b128 v102, v[226:229] offset:17408
	s_waitcnt vmcnt(11)
	ds_write_b128 v2, v[236:239] offset:34816
	s_waitcnt vmcnt(10)
	ds_write_b128 v104, v[232:235]
	s_waitcnt vmcnt(9)
	ds_write_b128 v104, v[248:251] offset:17408
	s_waitcnt vmcnt(8)
	ds_write_b128 v0, v[244:247] offset:34816
	v_add_u32_e32 v0, s14, v150
	s_waitcnt vmcnt(7)
	ds_write_b128 v0, v[252:255]
.Lseq_join_o:
	s_and_saveexec_b64 s[14:15], s[8:9]
	s_mul_i32 s35, s34, 0x1400
	v_add_u32_e32 v0, s35, v151
	ds_write_b128 v0, v[112:115]
	s_or_b64 exec, exec, s[14:15]
	s_and_saveexec_b64 s[14:15], s[10:11]
	v_lshl_add_u32 v0, s34, 9, v152
	ds_write_b128 v0, v[108:111]
	s_or_b64 exec, exec, s[14:15]
	s_cmp_eq_u32 s16, 61
	s_cbranch_scc1 .LBB0_1308_o
	v_lshl_add_u64 v[2:3], s[26:27], 0, v[148:149]
	v_lshl_add_u64 v[4:5], s[26:27], 0, v[144:145]
	global_load_dwordx4 v[222:225], v[2:3], off
	global_load_dwordx4 v[226:229], v[4:5], off
	v_lshl_add_u64 v[2:3], s[26:27], 0, v[146:147]
	v_lshl_add_u64 v[4:5], s[26:27], 0, v[142:143]
	global_load_dwordx4 v[236:239], v[2:3], off
	global_load_dwordx4 v[232:235], v[4:5], off
	v_lshl_add_u64 v[2:3], s[26:27], 0, v[138:139]
	v_lshl_add_u64 v[4:5], s[26:27], 0, v[140:141]
	global_load_dwordx4 v[248:251], v[2:3], off
	global_load_dwordx4 v[244:247], v[4:5], off
	v_lshl_add_u64 v[2:3], s[26:27], 0, v[134:135]
	global_load_dwordx4 v[252:255], v[2:3], off
	s_and_saveexec_b64 s[14:15], s[8:9]
	s_cbranch_execz .LBB0_1306_o
	v_lshl_add_u64 v[2:3], s[26:27], 0, v[136:137]
	global_load_dwordx4 v[112:115], v[2:3], off
	s_or_b64 exec, exec, s[14:15]
	s_and_saveexec_b64 s[14:15], s[10:11]
	s_cbranch_execz .LBB0_1308_o
	s_branch .LBB0_1307_o

; __global__ void __launch_bounds__(512, 2) mega(Params p) {
;     ...
;     final_norm_planar(out, p.in[23]);
; }
.LBB0_1994:
	s_endpgm
	.section	.rodata,"a",@progbits
	.p2align	6, 0x0
